# full stack: previous + steady-state loader iteration with exact counted vmcnt (two tiles really in flight) + double-buffered S-phase fragment reads in the paged MLA attention
# baseline (speedup 1.0000x reference)
.LBB0_1361:
	s_cmp_lt_u32 s64, 32
	s_cselect_b64 s[8:9], -1, 0
	s_or_b64 s[48:49], s[8:9], vcc
	s_and_saveexec_b64 s[8:9], s[48:49]
	s_cbranch_execz .LBB0_1360
	s_and_b32 s48, s64, 1
	s_mul_i32 s49, s48, 0x9400
	s_add_i32 s65, s49, 0
	v_add3_u32 v3, s65, v165, v172
	ds_read_b128 v[4:7], v3 offset:56832
	ds_read_b128 v[8:11], v173
	ds_read_b128 v[12:15], v173 offset:32
	ds_read_b128 v[176:179], v3 offset:56864
	ds_read_b128 v[204:207], v3 offset:56896
	ds_read_b128 v[226:229], v173 offset:64
	ds_read_b128 v[244:247], v173 offset:96
	ds_read_b128 v[248:251], v3 offset:56928
	s_mulk_i32 s48, 0xc00
	v_add3_u32 v175, v163, s48, v170
	s_cmp_eq_u32 s64, 32
	s_cselect_b64 s[54:55], -1, 0
	v_add_u32_e32 v199, 0x400, v175
	s_waitcnt lgkmcnt(6)
	v_mfma_f32_32x32x16_bf16 v[146:161], v[4:7], v[8:11], 0
	s_waitcnt lgkmcnt(4)
	v_mfma_f32_32x32x16_bf16 v[146:161], v[176:179], v[12:15], v[146:161]
	ds_read_b128 v[4:7], v3 offset:56960
	ds_read_b128 v[8:11], v173 offset:128
	ds_read_b128 v[12:15], v173 offset:160
	ds_read_b128 v[176:179], v3 offset:56992
	s_waitcnt lgkmcnt(6)
	v_mfma_f32_32x32x16_bf16 v[146:161], v[204:207], v[226:229], v[146:161]
	s_waitcnt lgkmcnt(4)
	v_mfma_f32_32x32x16_bf16 v[146:161], v[248:251], v[244:247], v[146:161]
	ds_read_b128 v[204:207], v3 offset:57024
	ds_read_b128 v[226:229], v173 offset:192
	ds_read_b128 v[244:247], v173 offset:224
	ds_read_b128 v[248:251], v3 offset:57056
	s_waitcnt lgkmcnt(6)
	v_mfma_f32_32x32x16_bf16 v[146:161], v[4:7], v[8:11], v[146:161]
	s_waitcnt lgkmcnt(4)
	v_mfma_f32_32x32x16_bf16 v[146:161], v[176:179], v[12:15], v[146:161]
	ds_read_b128 v[4:7], v3 offset:57088
	ds_read_b128 v[8:11], v173 offset:256
	ds_read_b128 v[12:15], v173 offset:288
	ds_read_b128 v[176:179], v3 offset:57120
	s_waitcnt lgkmcnt(6)
	v_mfma_f32_32x32x16_bf16 v[146:161], v[204:207], v[226:229], v[146:161]
	s_waitcnt lgkmcnt(4)
	v_mfma_f32_32x32x16_bf16 v[146:161], v[248:251], v[244:247], v[146:161]
	ds_read_b128 v[204:207], v3 offset:57152
	ds_read_b128 v[226:229], v173 offset:320
	ds_read_b128 v[244:247], v173 offset:352
	ds_read_b128 v[248:251], v3 offset:57184
	s_waitcnt lgkmcnt(6)
	v_mfma_f32_32x32x16_bf16 v[146:161], v[4:7], v[8:11], v[146:161]
	s_waitcnt lgkmcnt(4)
	v_mfma_f32_32x32x16_bf16 v[146:161], v[176:179], v[12:15], v[146:161]
	ds_read_b128 v[4:7], v3 offset:57216
	ds_read_b128 v[8:11], v173 offset:384
	ds_read_b128 v[12:15], v173 offset:416
	ds_read_b128 v[176:179], v3 offset:57248
	s_waitcnt lgkmcnt(6)
	v_mfma_f32_32x32x16_bf16 v[146:161], v[204:207], v[226:229], v[146:161]
	s_waitcnt lgkmcnt(4)
	v_mfma_f32_32x32x16_bf16 v[146:161], v[248:251], v[244:247], v[146:161]
	ds_read_b128 v[204:207], v3 offset:57280
	ds_read_b128 v[226:229], v173 offset:448
	ds_read_b128 v[244:247], v173 offset:480
	ds_read_b128 v[248:251], v3 offset:57312
	s_waitcnt lgkmcnt(6)
	v_mfma_f32_32x32x16_bf16 v[146:161], v[4:7], v[8:11], v[146:161]
	s_waitcnt lgkmcnt(4)
	v_mfma_f32_32x32x16_bf16 v[146:161], v[176:179], v[12:15], v[146:161]
	ds_read_b128 v[4:7], v3 offset:57344
	ds_read_b128 v[8:11], v173 offset:512
	ds_read_b128 v[12:15], v173 offset:544
	ds_read_b128 v[176:179], v3 offset:57376
	s_waitcnt lgkmcnt(6)
	v_mfma_f32_32x32x16_bf16 v[146:161], v[204:207], v[226:229], v[146:161]
	s_waitcnt lgkmcnt(4)
	v_mfma_f32_32x32x16_bf16 v[146:161], v[248:251], v[244:247], v[146:161]
	ds_read2_b32 v[204:205], v175 offset1:12
	ds_read2_b32 v[206:207], v175 offset0:24 offset1:36
	ds_read2_b32 v[226:227], v175 offset0:96 offset1:108
	ds_read2_b32 v[228:229], v175 offset0:120 offset1:132
	ds_read2_b32 v[244:245], v175 offset0:192 offset1:204
	ds_read2_b32 v[246:247], v175 offset0:216 offset1:228
	ds_read2_b32 v[248:249], v199 offset0:32 offset1:44
	ds_read2_b32 v[250:251], v199 offset0:56 offset1:68
	s_waitcnt lgkmcnt(10)
	v_mfma_f32_32x32x16_bf16 v[146:161], v[4:7], v[8:11], v[146:161]
	s_waitcnt lgkmcnt(8)
	v_mfma_f32_32x32x16_bf16 v[146:161], v[176:179], v[12:15], v[146:161]
	s_waitcnt lgkmcnt(4)
	s_nop 11
	v_mul_f32_e32 v3, v146, v204
	v_mul_f32_e32 v8, v205, v147
	v_mul_f32_e32 v9, v206, v148
	v_mul_f32_e32 v10, v207, v149
	v_mul_f32_e32 v11, v226, v150
	v_mul_f32_e32 v12, v227, v151
	v_mul_f32_e32 v13, v228, v152
	v_mul_f32_e32 v14, v229, v153
	s_waitcnt lgkmcnt(3)
	v_mul_f32_e32 v4, v244, v154
	v_mul_f32_e32 v5, v245, v155
	s_waitcnt lgkmcnt(2)
	v_mul_f32_e32 v6, v246, v156
	v_mul_f32_e32 v7, v247, v157
	s_waitcnt lgkmcnt(1)
	v_mul_f32_e32 v15, v248, v158
	v_mul_f32_e32 v16, v249, v159
	s_waitcnt lgkmcnt(0)
	v_mul_f32_e32 v17, v250, v160
	v_mul_f32_e32 v146, v251, v161
	s_cmp_eq_u32 s64, 32
	s_cbranch_scc1 .LmaskA
	v_mov_b32_e32 v147, v3

.LBB0_1371:
	s_cmp_lt_u32 s29, 2
	s_cbranch_scc1 .LslA_orig
	s_cmp_gt_u32 s29, 27
	s_cbranch_scc1 .LslA_orig
	s_waitcnt vmcnt(39)
	ds_write_b128 v1, v[14:17]
	s_waitcnt vmcnt(38)
	ds_write_b128 v179, v[100:103]
	s_waitcnt vmcnt(37)
	ds_write_b128 v180, v[116:119]
	s_waitcnt vmcnt(36)
	ds_write_b128 v181, v[6:9]
	s_waitcnt vmcnt(35)
	ds_write_b128 v182, v[10:13]
	s_waitcnt vmcnt(34)
	ds_write_b128 v183, v[108:111]
	s_waitcnt vmcnt(33)
	ds_write_b128 v184, v[112:115]
	s_waitcnt vmcnt(32)
	ds_write_b128 v185, v[120:123]
	s_waitcnt vmcnt(31)
	ds_write_b128 v186, v[124:127]
	s_waitcnt vmcnt(30)
	ds_write_b128 v187, v[128:131]
	s_waitcnt vmcnt(29)
	ds_write_b128 v188, v[132:135]
	s_waitcnt vmcnt(28)
	ds_write_b128 v189, v[136:139]
	s_waitcnt vmcnt(27)
	ds_write_b128 v190, v[140:143]
	s_waitcnt vmcnt(26)
	ds_write_b128 v191, v[144:147]
	s_waitcnt vmcnt(25)
	ds_write_b128 v192, v[152:155]
	s_waitcnt vmcnt(24)
	ds_write_b128 v193, v[156:159]
	s_waitcnt vmcnt(23)
	ds_write_b128 v194, v[160:163]
	s_waitcnt vmcnt(22)
	ds_write_b128 v195, v[164:167]
	s_waitcnt vmcnt(20)
	s_and_saveexec_b64 s[24:25], s[20:21]
	s_cbranch_execz .LslA_1374
	v_add_u32_e32 v3, 0, v178
	v_add_u32_e32 v3, 0x21200, v3
	ds_write_b128 v3, v[148:151]
	ds_write_b128 v3, v[104:107] offset:16
.LslA_1374:
	s_or_b64 exec, exec, s[24:25]
	s_nop 0
	v_mov_b32_e32 v107, 0
	v_mov_b32_e32 v9, 0
	v_mov_b32_e32 v8, 0
	v_mov_b32_e32 v7, 0
	v_mov_b32_e32 v6, 0
	v_mov_b32_e32 v13, 0
	v_mov_b32_e32 v12, 0
	v_mov_b32_e32 v11, 0
	v_mov_b32_e32 v10, 0
	v_mov_b32_e32 v111, 0
	v_mov_b32_e32 v110, 0
	v_mov_b32_e32 v109, 0
	v_mov_b32_e32 v108, 0
	v_mov_b32_e32 v115, 0
	v_mov_b32_e32 v114, 0
	v_mov_b32_e32 v113, 0
	v_mov_b32_e32 v112, 0
	v_mov_b32_e32 v123, 0
	v_mov_b32_e32 v122, 0
	v_mov_b32_e32 v121, 0
	v_mov_b32_e32 v120, 0
	v_mov_b32_e32 v127, 0
	v_mov_b32_e32 v126, 0
	v_mov_b32_e32 v125, 0
	v_mov_b32_e32 v124, 0
	v_mov_b32_e32 v131, 0
	v_mov_b32_e32 v130, 0
	v_mov_b32_e32 v129, 0
	v_mov_b32_e32 v128, 0
	v_mov_b32_e32 v135, 0
	v_mov_b32_e32 v134, 0
	v_mov_b32_e32 v133, 0
	v_mov_b32_e32 v132, 0
	v_mov_b32_e32 v139, 0
	v_mov_b32_e32 v138, 0
	v_mov_b32_e32 v137, 0
	v_mov_b32_e32 v136, 0
	v_mov_b32_e32 v143, 0
	v_mov_b32_e32 v142, 0
	v_mov_b32_e32 v141, 0
	v_mov_b32_e32 v140, 0
	v_mov_b32_e32 v147, 0
	v_mov_b32_e32 v146, 0
	v_mov_b32_e32 v145, 0
	v_mov_b32_e32 v144, 0
	v_mov_b32_e32 v155, 0
	v_mov_b32_e32 v154, 0
	v_mov_b32_e32 v153, 0
	v_mov_b32_e32 v152, 0
	v_mov_b32_e32 v159, 0
	v_mov_b32_e32 v158, 0
	v_mov_b32_e32 v157, 0
	v_mov_b32_e32 v156, 0
	v_mov_b32_e32 v163, 0
	v_mov_b32_e32 v162, 0
	v_mov_b32_e32 v161, 0
	v_mov_b32_e32 v160, 0
	v_mov_b32_e32 v167, 0
	v_mov_b32_e32 v166, 0
	v_mov_b32_e32 v165, 0
	v_mov_b32_e32 v164, 0
	v_mov_b64_e32 v[176:177], v[170:171]
	v_lshl_add_u64 v[4:5], s[92:93], 0, v[174:175]
	v_add_co_u32_e32 v6, vcc, 0x1d13e000, v4
	s_mov_b64 s[24:25], 0x30492000
	s_nop 0
	v_addc_co_u32_e32 v7, vcc, 0, v5, vcc
	v_add_co_u32_e32 v8, vcc, 0x1d13f000, v4
	v_mov_b32_e32 v3, v2
	s_nop 0
	v_addc_co_u32_e32 v9, vcc, 0, v5, vcc
	v_add_co_u32_e32 v10, vcc, 0x1d140000, v4
	global_load_dwordx4 v[14:17], v[6:7], off offset:3072
	global_load_dwordx4 v[100:103], v[8:9], off offset:1024
	v_addc_co_u32_e32 v11, vcc, 0, v5, vcc
	v_add_co_u32_e32 v104, vcc, 0x1d141000, v4
	global_load_dwordx4 v[116:119], v[8:9], off offset:3072
	s_nop 0
	global_load_dwordx4 v[6:9], v[10:11], off offset:1024
	v_addc_co_u32_e32 v105, vcc, 0, v5, vcc
	v_add_co_u32_e32 v124, vcc, 0x1d142000, v4
	global_load_dwordx4 v[10:13], v[10:11], off offset:3072
	s_nop 0
	global_load_dwordx4 v[108:111], v[104:105], off offset:1024
	v_addc_co_u32_e32 v125, vcc, 0, v5, vcc
	global_load_dwordx4 v[112:115], v[104:105], off offset:3072
	global_load_dwordx4 v[120:123], v[124:125], off offset:1024
	v_add_co_u32_e32 v104, vcc, 0x1d143000, v4
	s_nop 1
	v_addc_co_u32_e32 v105, vcc, 0, v5, vcc
	v_add_co_u32_e32 v140, vcc, 0x1d144000, v4
	global_load_dwordx4 v[124:127], v[124:125], off offset:3072
	s_nop 0
	global_load_dwordx4 v[128:131], v[104:105], off offset:1024
	v_addc_co_u32_e32 v141, vcc, 0, v5, vcc
	global_load_dwordx4 v[132:135], v[104:105], off offset:3072
	global_load_dwordx4 v[136:139], v[140:141], off offset:1024
	v_add_co_u32_e32 v104, vcc, 0x1d145000, v4
	s_nop 1
	v_addc_co_u32_e32 v105, vcc, 0, v5, vcc
	s_nop 0
	v_add_co_u32_e32 v148, vcc, 0x1d146000, v4
	global_load_dwordx4 v[140:143], v[140:141], off offset:3072
	s_nop 0
	global_load_dwordx4 v[144:147], v[104:105], off offset:1024
	v_addc_co_u32_e32 v149, vcc, 0, v5, vcc
	v_add_co_u32_e32 v4, vcc, 0x1d147000, v4
	global_load_dwordx4 v[152:155], v[104:105], off offset:3072
	global_load_dwordx4 v[156:159], v[148:149], off offset:1024
	v_addc_co_u32_e32 v5, vcc, 0, v5, vcc
	global_load_dwordx4 v[160:163], v[148:149], off offset:3072
	global_load_dwordx4 v[164:167], v[4:5], off offset:1024
	v_lshl_add_u64 v[4:5], s[92:93], 0, v[172:173]
	v_lshl_add_u64 v[176:177], v[4:5], 0, s[24:25]
	v_mov_b32_e32 v4, v2
	v_mov_b32_e32 v5, v2
	v_mov_b64_e32 v[150:151], v[4:5]
	v_mov_b64_e32 v[148:149], v[2:3]
	s_and_saveexec_b64 s[24:25], s[20:21]
	s_cbranch_execz .LslA_1390
	global_load_dwordx4 v[148:151], v[176:177], off

.LslA_1393:
	s_or_b64 exec, exec, s[26:27]
	s_waitcnt lgkmcnt(0)
	s_barrier
	s_waitcnt vmcnt(39)
	ds_write_b128 v210, v[24:27] offset:56832
	s_waitcnt vmcnt(38)
	ds_write_b128 v211, v[20:23] offset:56832
	s_waitcnt vmcnt(37)
	ds_write_b128 v212, v[28:31] offset:56832
	s_waitcnt vmcnt(36)
	ds_write_b128 v213, v[32:35] offset:56832
	s_waitcnt vmcnt(35)
	ds_write_b128 v214, v[36:39] offset:56832
	s_waitcnt vmcnt(34)
	ds_write_b128 v215, v[40:43] offset:56832
	s_waitcnt vmcnt(33)
	ds_write_b128 v216, v[44:47] offset:56832
	s_waitcnt vmcnt(32)
	ds_write_b128 v217, v[48:51] offset:56832
	s_waitcnt vmcnt(31)
	ds_write_b128 v218, v[56:59] offset:56832
	s_waitcnt vmcnt(30)
	ds_write_b128 v219, v[60:63] offset:56832
	s_waitcnt vmcnt(29)
	ds_write_b128 v220, v[64:67] offset:56832
	s_waitcnt vmcnt(28)
	ds_write_b128 v221, v[68:71] offset:56832
	s_waitcnt vmcnt(27)
	ds_write_b128 v222, v[72:75] offset:56832
	s_waitcnt vmcnt(26)
	ds_write_b128 v223, v[76:79] offset:56832
	s_waitcnt vmcnt(25)
	ds_write_b128 v224, v[80:83] offset:56832
	s_waitcnt vmcnt(24)
	ds_write_b128 v225, v[84:87] offset:56832
	s_waitcnt vmcnt(23)
	ds_write_b128 v226, v[88:91] offset:56832
	s_waitcnt vmcnt(22)
	ds_write_b128 v227, v[92:95] offset:56832
	s_waitcnt vmcnt(20)
	s_and_saveexec_b64 s[0:1], s[20:21]
	s_cbranch_execz .LslA_1398
	v_add_u32_e32 v3, 0, v178
	v_add_u32_e32 v3, 0x20600, v3
	ds_write_b128 v3, v[52:55]
	ds_write_b128 v3, v[96:99] offset:16
.LslA_1398:
	s_or_b64 exec, exec, s[0:1]
	s_mov_b64 s[0:1], 0
	v_lshl_add_u64 v[4:5], s[92:93], 0, v[174:175]
	s_nop 0
	v_add_co_u32_e32 v20, vcc, 0x1d147000, v4
	s_mov_b64 s[0:1], 0x30492c00
	s_nop 0
	v_addc_co_u32_e32 v21, vcc, 0, v5, vcc
	s_nop 0
	v_add_co_u32_e32 v28, vcc, 0x1d148000, v4
	v_mov_b32_e32 v3, v2
	s_nop 0
	v_addc_co_u32_e32 v29, vcc, 0, v5, vcc
	s_nop 0
	v_add_co_u32_e32 v36, vcc, 0x1d149000, v4
	global_load_dwordx4 v[24:27], v[20:21], off offset:3072
	s_nop 0
	global_load_dwordx4 v[20:23], v[28:29], off offset:1024
	v_addc_co_u32_e32 v37, vcc, 0, v5, vcc
	s_nop 0
	v_add_co_u32_e32 v44, vcc, 0x1d14a000, v4
	global_load_dwordx4 v[28:31], v[28:29], off offset:3072
	s_nop 0
	global_load_dwordx4 v[32:35], v[36:37], off offset:1024
	v_addc_co_u32_e32 v45, vcc, 0, v5, vcc
	s_nop 0
	v_add_co_u32_e32 v52, vcc, 0x1d14b000, v4
	global_load_dwordx4 v[36:39], v[36:37], off offset:3072
	s_nop 0
	global_load_dwordx4 v[40:43], v[44:45], off offset:1024
	v_addc_co_u32_e32 v53, vcc, 0, v5, vcc
	v_add_co_u32_e32 v54, vcc, 0x1d14c000, v4
	global_load_dwordx4 v[44:47], v[44:45], off offset:3072
	s_nop 0
	global_load_dwordx4 v[48:51], v[52:53], off offset:1024
	v_addc_co_u32_e32 v55, vcc, 0, v5, vcc
	global_load_dwordx4 v[56:59], v[52:53], off offset:3072
	global_load_dwordx4 v[60:63], v[54:55], off offset:1024
	v_add_co_u32_e32 v52, vcc, 0x1d14d000, v4
	s_nop 1
	v_addc_co_u32_e32 v53, vcc, 0, v5, vcc
	global_load_dwordx4 v[64:67], v[54:55], off offset:3072
	global_load_dwordx4 v[68:71], v[52:53], off offset:1024
	v_add_co_u32_e32 v54, vcc, 0x1d14e000, v4
	s_nop 1
	v_addc_co_u32_e32 v55, vcc, 0, v5, vcc
	global_load_dwordx4 v[72:75], v[52:53], off offset:3072
	global_load_dwordx4 v[76:79], v[54:55], off offset:1024
	v_add_co_u32_e32 v52, vcc, 0x1d14f000, v4
	s_nop 1
	v_addc_co_u32_e32 v53, vcc, 0, v5, vcc
	v_add_co_u32_e32 v4, vcc, 0x1d150000, v4
	global_load_dwordx4 v[80:83], v[54:55], off offset:3072
	global_load_dwordx4 v[84:87], v[52:53], off offset:1024
	v_addc_co_u32_e32 v5, vcc, 0, v5, vcc
	global_load_dwordx4 v[88:91], v[52:53], off offset:3072
	global_load_dwordx4 v[92:95], v[4:5], off offset:1024
	v_lshl_add_u64 v[4:5], s[92:93], 0, v[172:173]
	v_lshl_add_u64 v[176:177], v[4:5], 0, s[0:1]
	v_mov_b32_e32 v4, v2
	v_mov_b32_e32 v5, v2
	v_mov_b64_e32 v[54:55], v[4:5]
	v_mov_b64_e32 v[52:53], v[2:3]
	s_and_saveexec_b64 s[0:1], s[20:21]
	s_cbranch_execz .LslA_1414
	global_load_dwordx4 v[52:55], v[176:177], off

.LslA_1415:
	v_mov_b32_e32 v4, v2
	v_mov_b32_e32 v5, v2
	v_mov_b32_e32 v3, v2
	v_mov_b64_e32 v[98:99], v[4:5]
	v_mov_b64_e32 v[96:97], v[2:3]
	s_and_saveexec_b64 s[24:25], s[0:1]
	s_cbranch_execz .LBB0_1368
	global_load_dwordx4 v[96:99], v[176:177], off offset:16
	s_branch .LBB0_1368
.LslA_orig:
	s_add_i32 s24, s29, 1
	s_cmp_lt_u32 s24, s62
	s_cselect_b64 s[0:1], -1, 0
	s_cmp_ge_u32 s24, s62
	s_cbranch_scc1 .LBB0_1375
	s_waitcnt vmcnt(0)
	ds_write_b128 v1, v[14:17]
	s_waitcnt vmcnt(34)
	ds_write_b128 v179, v[100:103]
	s_waitcnt vmcnt(33)
	ds_write_b128 v180, v[116:119]
	s_waitcnt vmcnt(32)
	ds_write_b128 v181, v[6:9]
	s_waitcnt vmcnt(31)
	ds_write_b128 v182, v[10:13]
	s_waitcnt vmcnt(30)
	ds_write_b128 v183, v[108:111]
	s_waitcnt vmcnt(29)
	ds_write_b128 v184, v[112:115]
	s_waitcnt vmcnt(28)
	ds_write_b128 v185, v[120:123]
	s_waitcnt vmcnt(27)
	ds_write_b128 v186, v[124:127]
	s_waitcnt vmcnt(26)
	ds_write_b128 v187, v[128:131]
	s_waitcnt vmcnt(25)
	ds_write_b128 v188, v[132:135]
	s_waitcnt vmcnt(24)
	ds_write_b128 v189, v[136:139]
	s_waitcnt vmcnt(23)
	ds_write_b128 v190, v[140:143]
	s_waitcnt vmcnt(22)
	ds_write_b128 v191, v[144:147]
	s_waitcnt vmcnt(21)
	ds_write_b128 v192, v[152:155]
	s_waitcnt vmcnt(20)
	ds_write_b128 v193, v[156:159]
	s_waitcnt vmcnt(19)
	ds_write_b128 v194, v[160:163]
	s_waitcnt vmcnt(18)
	ds_write_b128 v195, v[164:167]
	s_and_saveexec_b64 s[24:25], s[20:21]
	s_cbranch_execz .LBB0_1374
	v_add_u32_e32 v3, 0, v178
	v_add_u32_e32 v3, 0x21200, v3
	ds_write_b128 v3, v[148:151]
	ds_write_b128 v3, v[104:107] offset:16

.LBB0_1543:
	s_cmp_lt_u32 s65, 32
	s_cselect_b64 s[8:9], -1, 0
	s_or_b64 s[48:49], s[8:9], vcc
	s_and_saveexec_b64 s[8:9], s[48:49]
	s_cbranch_execz .LBB0_1542
	s_and_b32 s48, s65, 1
	s_mul_i32 s49, s48, 0x9400
	s_add_i32 s67, s49, 0
	v_add3_u32 v3, s67, v165, v172
	ds_read_b128 v[4:7], v3 offset:56832
	ds_read_b128 v[8:11], v173
	ds_read_b128 v[12:15], v173 offset:32
	ds_read_b128 v[176:179], v3 offset:56864
	ds_read_b128 v[204:207], v3 offset:56896
	ds_read_b128 v[226:229], v173 offset:64
	ds_read_b128 v[244:247], v173 offset:96
	ds_read_b128 v[248:251], v3 offset:56928
	s_mulk_i32 s48, 0xc00
	v_add3_u32 v175, v163, s48, v170
	s_cmp_eq_u32 s65, 32
	s_cselect_b64 s[74:75], -1, 0
	v_add_u32_e32 v199, 0x400, v175
	s_waitcnt lgkmcnt(6)
	v_mfma_f32_32x32x16_bf16 v[146:161], v[4:7], v[8:11], 0
	s_waitcnt lgkmcnt(4)
	v_mfma_f32_32x32x16_bf16 v[146:161], v[176:179], v[12:15], v[146:161]
	ds_read_b128 v[4:7], v3 offset:56960
	ds_read_b128 v[8:11], v173 offset:128
	ds_read_b128 v[12:15], v173 offset:160
	ds_read_b128 v[176:179], v3 offset:56992
	s_waitcnt lgkmcnt(6)
	v_mfma_f32_32x32x16_bf16 v[146:161], v[204:207], v[226:229], v[146:161]
	s_waitcnt lgkmcnt(4)
	v_mfma_f32_32x32x16_bf16 v[146:161], v[248:251], v[244:247], v[146:161]
	ds_read_b128 v[204:207], v3 offset:57024
	ds_read_b128 v[226:229], v173 offset:192
	ds_read_b128 v[244:247], v173 offset:224
	ds_read_b128 v[248:251], v3 offset:57056
	s_waitcnt lgkmcnt(6)
	v_mfma_f32_32x32x16_bf16 v[146:161], v[4:7], v[8:11], v[146:161]
	s_waitcnt lgkmcnt(4)
	v_mfma_f32_32x32x16_bf16 v[146:161], v[176:179], v[12:15], v[146:161]
	ds_read_b128 v[4:7], v3 offset:57088
	ds_read_b128 v[8:11], v173 offset:256
	ds_read_b128 v[12:15], v173 offset:288
	ds_read_b128 v[176:179], v3 offset:57120
	s_waitcnt lgkmcnt(6)
	v_mfma_f32_32x32x16_bf16 v[146:161], v[204:207], v[226:229], v[146:161]
	s_waitcnt lgkmcnt(4)
	v_mfma_f32_32x32x16_bf16 v[146:161], v[248:251], v[244:247], v[146:161]
	ds_read_b128 v[204:207], v3 offset:57152
	ds_read_b128 v[226:229], v173 offset:320
	ds_read_b128 v[244:247], v173 offset:352
	ds_read_b128 v[248:251], v3 offset:57184
	s_waitcnt lgkmcnt(6)
	v_mfma_f32_32x32x16_bf16 v[146:161], v[4:7], v[8:11], v[146:161]
	s_waitcnt lgkmcnt(4)
	v_mfma_f32_32x32x16_bf16 v[146:161], v[176:179], v[12:15], v[146:161]
	ds_read_b128 v[4:7], v3 offset:57216
	ds_read_b128 v[8:11], v173 offset:384
	ds_read_b128 v[12:15], v173 offset:416
	ds_read_b128 v[176:179], v3 offset:57248
	s_waitcnt lgkmcnt(6)
	v_mfma_f32_32x32x16_bf16 v[146:161], v[204:207], v[226:229], v[146:161]
	s_waitcnt lgkmcnt(4)
	v_mfma_f32_32x32x16_bf16 v[146:161], v[248:251], v[244:247], v[146:161]
	ds_read_b128 v[204:207], v3 offset:57280
	ds_read_b128 v[226:229], v173 offset:448
	ds_read_b128 v[244:247], v173 offset:480
	ds_read_b128 v[248:251], v3 offset:57312
	s_waitcnt lgkmcnt(6)
	v_mfma_f32_32x32x16_bf16 v[146:161], v[4:7], v[8:11], v[146:161]
	s_waitcnt lgkmcnt(4)
	v_mfma_f32_32x32x16_bf16 v[146:161], v[176:179], v[12:15], v[146:161]
	ds_read_b128 v[4:7], v3 offset:57344
	ds_read_b128 v[8:11], v173 offset:512
	ds_read_b128 v[12:15], v173 offset:544
	ds_read_b128 v[176:179], v3 offset:57376
	s_waitcnt lgkmcnt(6)
	v_mfma_f32_32x32x16_bf16 v[146:161], v[204:207], v[226:229], v[146:161]
	s_waitcnt lgkmcnt(4)
	v_mfma_f32_32x32x16_bf16 v[146:161], v[248:251], v[244:247], v[146:161]
	ds_read2_b32 v[204:205], v175 offset1:12
	ds_read2_b32 v[206:207], v175 offset0:24 offset1:36
	ds_read2_b32 v[226:227], v175 offset0:96 offset1:108
	ds_read2_b32 v[228:229], v175 offset0:120 offset1:132
	ds_read2_b32 v[244:245], v175 offset0:192 offset1:204
	ds_read2_b32 v[246:247], v175 offset0:216 offset1:228
	ds_read2_b32 v[248:249], v199 offset0:32 offset1:44
	ds_read2_b32 v[250:251], v199 offset0:56 offset1:68
	s_waitcnt lgkmcnt(10)
	v_mfma_f32_32x32x16_bf16 v[146:161], v[4:7], v[8:11], v[146:161]
	s_waitcnt lgkmcnt(8)
	v_mfma_f32_32x32x16_bf16 v[146:161], v[176:179], v[12:15], v[146:161]
	s_waitcnt lgkmcnt(4)
	s_nop 11
	v_mul_f32_e32 v3, v146, v204
	v_mul_f32_e32 v8, v205, v147
	v_mul_f32_e32 v9, v206, v148
	v_mul_f32_e32 v10, v207, v149
	v_mul_f32_e32 v11, v226, v150
	v_mul_f32_e32 v12, v227, v151
	v_mul_f32_e32 v13, v228, v152
	v_mul_f32_e32 v14, v229, v153
	s_waitcnt lgkmcnt(3)
	v_mul_f32_e32 v4, v244, v154
	v_mul_f32_e32 v5, v245, v155
	s_waitcnt lgkmcnt(2)
	v_mul_f32_e32 v6, v246, v156
	v_mul_f32_e32 v7, v247, v157
	s_waitcnt lgkmcnt(1)
	v_mul_f32_e32 v15, v248, v158
	v_mul_f32_e32 v16, v249, v159
	s_waitcnt lgkmcnt(0)
	v_mul_f32_e32 v17, v250, v160
	v_mul_f32_e32 v146, v251, v161
	s_cmp_eq_u32 s65, 32
	s_cbranch_scc1 .LmaskB
	v_mov_b32_e32 v147, v3

.LslB_1597:
	v_mov_b32_e32 v4, v2
	v_mov_b32_e32 v5, v2
	v_mov_b32_e32 v3, v2
	v_mov_b64_e32 v[98:99], v[4:5]
	v_mov_b64_e32 v[96:97], v[2:3]
	s_and_saveexec_b64 s[24:25], s[0:1]
	s_cbranch_execz .LBB0_1550
	global_load_dwordx4 v[96:99], v[176:177], off offset:16
	s_branch .LBB0_1550
.LslB_orig:
	s_add_i32 s24, s29, 1
	s_cmp_lt_u32 s24, s64
	s_cselect_b64 s[0:1], -1, 0
	s_cmp_ge_u32 s24, s64
	s_cbranch_scc1 .LBB0_1557
	s_waitcnt vmcnt(0)
	ds_write_b128 v1, v[14:17]
	s_waitcnt vmcnt(34)
	ds_write_b128 v179, v[100:103]
	s_waitcnt vmcnt(33)
	ds_write_b128 v180, v[116:119]
	s_waitcnt vmcnt(32)
	ds_write_b128 v181, v[6:9]
	s_waitcnt vmcnt(31)
	ds_write_b128 v182, v[10:13]
	s_waitcnt vmcnt(30)
	ds_write_b128 v183, v[108:111]
	s_waitcnt vmcnt(29)
	ds_write_b128 v184, v[112:115]
	s_waitcnt vmcnt(28)
	ds_write_b128 v185, v[120:123]
	s_waitcnt vmcnt(27)
	ds_write_b128 v186, v[124:127]
	s_waitcnt vmcnt(26)
	ds_write_b128 v187, v[128:131]
	s_waitcnt vmcnt(25)
	ds_write_b128 v188, v[132:135]
	s_waitcnt vmcnt(24)
	ds_write_b128 v189, v[136:139]
	s_waitcnt vmcnt(23)
	ds_write_b128 v190, v[140:143]
	s_waitcnt vmcnt(22)
	ds_write_b128 v191, v[144:147]
	s_waitcnt vmcnt(21)
	ds_write_b128 v192, v[152:155]
	s_waitcnt vmcnt(20)
	ds_write_b128 v193, v[156:159]
	s_waitcnt vmcnt(19)
	ds_write_b128 v194, v[160:163]
	s_waitcnt vmcnt(18)
	ds_write_b128 v195, v[164:167]
	s_and_saveexec_b64 s[24:25], s[20:21]
	s_cbranch_execz .LBB0_1556
	v_add_u32_e32 v3, 0, v178
	v_add_u32_e32 v3, 0x21200, v3
	ds_write_b128 v3, v[148:151]
	ds_write_b128 v3, v[104:107] offset:16
